# P7 K loop MFMA operands swapped (transposed 16x16 blocks) + SwiGLU epilogue with one rstd per lane and 8-byte stores (16 per wave)
# baseline (speedup 1.0000x reference)
; DI float fexp2(float x) { return __builtin_amdgcn_exp2f(x); }
;     ...
;   if constexpr (EPI == EPI_GU) {
;     __syncthreads();
;     const float* rstdL = (const float*)(smem + SMEM_RSTD);
; #pragma unroll
;     for (int ai = 0; ai < 2; ++ai)
; #pragma unroll
;       for (int m = 0; m < 4; ++m) {
;         const int rowb = ai * 128 + wr * 64 + m * 16 + fq * 4;
;         const f32x4 rs4 = *(const f32x4*)(rstdL + rowb);
; #pragma unroll
;         for (int bj = 0; bj < 2; ++bj) {
;           bf16_t* op = e.out + (size_t)(m0 + rowb) * e.ldo + ((n0 + bj * 128 + wc * 32) >> 1) + fr;
; #pragma unroll
;           for (int j = 0; j < 4; ++j) {
;             const float g = acc[ai][bj][m][0][j] * rs4[j], u = acc[ai][bj][m][1][j] * rs4[j];
;             const float rv = g * __builtin_amdgcn_rcpf(1.f + fexp2(-g * LOG2E)) * u;
;             op[(size_t)j * e.ldo] = (bf16_t)(pack2(rv, 0.f) & 0xffffu);
;           }
;         }
;       }
;     __syncthreads();
;     return;
;   }
.LBB0_1243:
	s_or_b64 exec, exec, s[2:3]
	v_lshl_or_b32 v135, v148, 2, v149
	v_mov_b32_e32 v144, 0x21010
	v_lshl_add_u32 v134, v135, 2, v144
	s_waitcnt vmcnt(8) lgkmcnt(0)
	s_barrier
	v_add_u32_e32 v196, v149, v147
	v_lshl_add_u32 v134, v196, 2, v144
	ds_read_b32 v150, v134
	ds_read_b32 v152, v134 offset:64
	ds_read_b32 v154, v134 offset:128
	ds_read_b32 v156, v134 offset:192
	ds_read_b32 v158, v134 offset:512
	ds_read_b32 v160, v134 offset:576
	ds_read_b32 v162, v134 offset:640
	ds_read_b32 v164, v134 offset:704
	s_movk_i32 s13, 0x1600
	v_add_u32_e32 v190, s27, v196
	v_mul_lo_u32 v190, v190, s13
	v_lshl_or_b32 v191, v146, 5, s0
	v_ashrrev_i32_e32 v191, 1, v191
	v_lshl_add_u32 v191, v148, 2, v191
	v_lshl_add_u32 v190, v191, 1, v190
	s_mov_b32 s12, 0xbfb8aa3b
	s_waitcnt lgkmcnt(7)
	v_pk_mul_f32 v[128:129], v[128:129], v[150:151] op_sel_hi:[1,0]
	v_pk_mul_f32 v[130:131], v[130:131], v[150:151] op_sel_hi:[1,0]
	v_pk_mul_f32 v[120:121], v[120:121], v[150:151] op_sel_hi:[1,0]
	v_pk_mul_f32 v[122:123], v[122:123], v[150:151] op_sel_hi:[1,0]
	v_pk_mul_f32 v[182:183], v[128:129], s[12:13] op_sel_hi:[1,0]
	v_pk_mul_f32 v[184:185], v[130:131], s[12:13] op_sel_hi:[1,0]
	v_pk_mul_f32 v[186:187], v[120:121], s[12:13] op_sel_hi:[1,0]
	v_pk_mul_f32 v[188:189], v[122:123], s[12:13] op_sel_hi:[1,0]
	v_exp_f32_e32 v182, v182
	v_exp_f32_e32 v183, v183
	v_exp_f32_e32 v184, v184
	v_exp_f32_e32 v185, v185
	v_exp_f32_e32 v186, v186
	v_exp_f32_e32 v187, v187
	v_exp_f32_e32 v188, v188
	v_exp_f32_e32 v189, v189
	v_mov_b32_e32 v192, v190
	v_pk_add_f32 v[182:183], v[182:183], 1.0 op_sel_hi:[1,0]
	v_pk_add_f32 v[184:185], v[184:185], 1.0 op_sel_hi:[1,0]
	v_pk_add_f32 v[186:187], v[186:187], 1.0 op_sel_hi:[1,0]
	v_pk_add_f32 v[188:189], v[188:189], 1.0 op_sel_hi:[1,0]
	v_rcp_f32_e32 v182, v182
	v_rcp_f32_e32 v183, v183
	v_rcp_f32_e32 v184, v184
	v_rcp_f32_e32 v185, v185
	v_rcp_f32_e32 v186, v186
	v_rcp_f32_e32 v187, v187
	v_rcp_f32_e32 v188, v188
	v_rcp_f32_e32 v189, v189
	v_pk_mul_f32 v[124:125], v[124:125], v[150:151] op_sel_hi:[1,0]
	v_pk_mul_f32 v[126:127], v[126:127], v[150:151] op_sel_hi:[1,0]
	v_pk_mul_f32 v[116:117], v[116:117], v[150:151] op_sel_hi:[1,0]
	v_pk_mul_f32 v[118:119], v[118:119], v[150:151] op_sel_hi:[1,0]
	v_pk_mul_f32 v[128:129], v[128:129], v[182:183]
	v_pk_mul_f32 v[130:131], v[130:131], v[184:185]
	v_pk_mul_f32 v[120:121], v[120:121], v[186:187]
	v_pk_mul_f32 v[122:123], v[122:123], v[188:189]
	v_pk_mul_f32 v[124:125], v[124:125], v[128:129]
	v_pk_mul_f32 v[126:127], v[126:127], v[130:131]
	v_pk_mul_f32 v[116:117], v[116:117], v[120:121]
	v_pk_mul_f32 v[118:119], v[118:119], v[122:123]
	v_cvt_pk_bf16_f32 v124, v124, v125
	v_cvt_pk_bf16_f32 v125, v126, v127
	v_cvt_pk_bf16_f32 v116, v116, v117
	v_cvt_pk_bf16_f32 v117, v118, v119
	global_store_dwordx2 v192, v[124:125], s[30:31]
	global_store_dwordx2 v192, v[116:117], s[30:31] offset:128
	s_waitcnt lgkmcnt(6)
	v_pk_mul_f32 v[112:113], v[112:113], v[152:153] op_sel_hi:[1,0]
	v_pk_mul_f32 v[114:115], v[114:115], v[152:153] op_sel_hi:[1,0]
	v_pk_mul_f32 v[104:105], v[104:105], v[152:153] op_sel_hi:[1,0]
	v_pk_mul_f32 v[106:107], v[106:107], v[152:153] op_sel_hi:[1,0]
	v_pk_mul_f32 v[182:183], v[112:113], s[12:13] op_sel_hi:[1,0]
	v_pk_mul_f32 v[184:185], v[114:115], s[12:13] op_sel_hi:[1,0]
	v_pk_mul_f32 v[186:187], v[104:105], s[12:13] op_sel_hi:[1,0]
	v_pk_mul_f32 v[188:189], v[106:107], s[12:13] op_sel_hi:[1,0]
	v_exp_f32_e32 v182, v182
	v_exp_f32_e32 v183, v183
	v_exp_f32_e32 v184, v184
	v_exp_f32_e32 v185, v185
	v_exp_f32_e32 v186, v186
	v_exp_f32_e32 v187, v187
	v_exp_f32_e32 v188, v188
	v_exp_f32_e32 v189, v189
	v_add_u32_e32 v192, 0x16000, v190
	v_pk_add_f32 v[182:183], v[182:183], 1.0 op_sel_hi:[1,0]
	v_pk_add_f32 v[184:185], v[184:185], 1.0 op_sel_hi:[1,0]
	v_pk_add_f32 v[186:187], v[186:187], 1.0 op_sel_hi:[1,0]
	v_pk_add_f32 v[188:189], v[188:189], 1.0 op_sel_hi:[1,0]
	v_rcp_f32_e32 v182, v182
	v_rcp_f32_e32 v183, v183
	v_rcp_f32_e32 v184, v184
	v_rcp_f32_e32 v185, v185
	v_rcp_f32_e32 v186, v186
	v_rcp_f32_e32 v187, v187
	v_rcp_f32_e32 v188, v188
	v_rcp_f32_e32 v189, v189
	v_pk_mul_f32 v[108:109], v[108:109], v[152:153] op_sel_hi:[1,0]
	v_pk_mul_f32 v[110:111], v[110:111], v[152:153] op_sel_hi:[1,0]
	v_pk_mul_f32 v[100:101], v[100:101], v[152:153] op_sel_hi:[1,0]
	v_pk_mul_f32 v[102:103], v[102:103], v[152:153] op_sel_hi:[1,0]
	v_pk_mul_f32 v[112:113], v[112:113], v[182:183]
	v_pk_mul_f32 v[114:115], v[114:115], v[184:185]
	v_pk_mul_f32 v[104:105], v[104:105], v[186:187]
	v_pk_mul_f32 v[106:107], v[106:107], v[188:189]
	v_pk_mul_f32 v[108:109], v[108:109], v[112:113]
	v_pk_mul_f32 v[110:111], v[110:111], v[114:115]
	v_pk_mul_f32 v[100:101], v[100:101], v[104:105]
	v_pk_mul_f32 v[102:103], v[102:103], v[106:107]
	v_cvt_pk_bf16_f32 v108, v108, v109
	v_cvt_pk_bf16_f32 v109, v110, v111
	v_cvt_pk_bf16_f32 v100, v100, v101
	v_cvt_pk_bf16_f32 v101, v102, v103
	global_store_dwordx2 v192, v[108:109], s[30:31]
	global_store_dwordx2 v192, v[100:101], s[30:31] offset:128
	s_waitcnt lgkmcnt(5)
; DI float fexp2(float x) { return __builtin_amdgcn_exp2f(x); }
;     ...
; #pragma unroll
;     for (int ai = 0; ai < 2; ++ai)
; #pragma unroll
;       for (int m = 0; m < 4; ++m) {
;         const int rowb = ai * 128 + wr * 64 + m * 16 + fq * 4;
;         const f32x4 rs4 = *(const f32x4*)(rstdL + rowb);
; #pragma unroll
;         for (int bj = 0; bj < 2; ++bj) {
;           bf16_t* op = e.out + (size_t)(m0 + rowb) * e.ldo + ((n0 + bj * 128 + wc * 32) >> 1) + fr;
; #pragma unroll
;           for (int j = 0; j < 4; ++j) {
;             const float g = acc[ai][bj][m][0][j] * rs4[j], u = acc[ai][bj][m][1][j] * rs4[j];
;             const float rv = g * __builtin_amdgcn_rcpf(1.f + fexp2(-g * LOG2E)) * u;
;             op[(size_t)j * e.ldo] = (bf16_t)(pack2(rv, 0.f) & 0xffffu);
;           }
;         }
;       }
	v_pk_mul_f32 v[96:97], v[96:97], v[154:155] op_sel_hi:[1,0]
	v_pk_mul_f32 v[98:99], v[98:99], v[154:155] op_sel_hi:[1,0]
	v_pk_mul_f32 v[88:89], v[88:89], v[154:155] op_sel_hi:[1,0]
	v_pk_mul_f32 v[90:91], v[90:91], v[154:155] op_sel_hi:[1,0]
	v_pk_mul_f32 v[182:183], v[96:97], s[12:13] op_sel_hi:[1,0]
	v_pk_mul_f32 v[184:185], v[98:99], s[12:13] op_sel_hi:[1,0]
	v_pk_mul_f32 v[186:187], v[88:89], s[12:13] op_sel_hi:[1,0]
	v_pk_mul_f32 v[188:189], v[90:91], s[12:13] op_sel_hi:[1,0]
	v_exp_f32_e32 v182, v182
	v_exp_f32_e32 v183, v183
	v_exp_f32_e32 v184, v184
	v_exp_f32_e32 v185, v185
	v_exp_f32_e32 v186, v186
	v_exp_f32_e32 v187, v187
	v_exp_f32_e32 v188, v188
	v_exp_f32_e32 v189, v189
	v_add_u32_e32 v192, 0x2c000, v190
	v_pk_add_f32 v[182:183], v[182:183], 1.0 op_sel_hi:[1,0]
	v_pk_add_f32 v[184:185], v[184:185], 1.0 op_sel_hi:[1,0]
	v_pk_add_f32 v[186:187], v[186:187], 1.0 op_sel_hi:[1,0]
	v_pk_add_f32 v[188:189], v[188:189], 1.0 op_sel_hi:[1,0]
	v_rcp_f32_e32 v182, v182
	v_rcp_f32_e32 v183, v183
	v_rcp_f32_e32 v184, v184
	v_rcp_f32_e32 v185, v185
	v_rcp_f32_e32 v186, v186
	v_rcp_f32_e32 v187, v187
	v_rcp_f32_e32 v188, v188
	v_rcp_f32_e32 v189, v189
	v_pk_mul_f32 v[92:93], v[92:93], v[154:155] op_sel_hi:[1,0]
	v_pk_mul_f32 v[94:95], v[94:95], v[154:155] op_sel_hi:[1,0]
	v_pk_mul_f32 v[84:85], v[84:85], v[154:155] op_sel_hi:[1,0]
	v_pk_mul_f32 v[86:87], v[86:87], v[154:155] op_sel_hi:[1,0]
	v_pk_mul_f32 v[96:97], v[96:97], v[182:183]
	v_pk_mul_f32 v[98:99], v[98:99], v[184:185]
	v_pk_mul_f32 v[88:89], v[88:89], v[186:187]
	v_pk_mul_f32 v[90:91], v[90:91], v[188:189]
	v_pk_mul_f32 v[92:93], v[92:93], v[96:97]
	v_pk_mul_f32 v[94:95], v[94:95], v[98:99]
	v_pk_mul_f32 v[84:85], v[84:85], v[88:89]
	v_pk_mul_f32 v[86:87], v[86:87], v[90:91]
	v_cvt_pk_bf16_f32 v92, v92, v93
	v_cvt_pk_bf16_f32 v93, v94, v95
	v_cvt_pk_bf16_f32 v84, v84, v85
	v_cvt_pk_bf16_f32 v85, v86, v87
	global_store_dwordx2 v192, v[92:93], s[30:31]
	global_store_dwordx2 v192, v[84:85], s[30:31] offset:128
	s_waitcnt lgkmcnt(4)
	v_pk_mul_f32 v[80:81], v[80:81], v[156:157] op_sel_hi:[1,0]
	v_pk_mul_f32 v[82:83], v[82:83], v[156:157] op_sel_hi:[1,0]
	v_pk_mul_f32 v[72:73], v[72:73], v[156:157] op_sel_hi:[1,0]
	v_pk_mul_f32 v[74:75], v[74:75], v[156:157] op_sel_hi:[1,0]
	v_pk_mul_f32 v[182:183], v[80:81], s[12:13] op_sel_hi:[1,0]
	v_pk_mul_f32 v[184:185], v[82:83], s[12:13] op_sel_hi:[1,0]
	v_pk_mul_f32 v[186:187], v[72:73], s[12:13] op_sel_hi:[1,0]
	v_pk_mul_f32 v[188:189], v[74:75], s[12:13] op_sel_hi:[1,0]
	v_exp_f32_e32 v182, v182
	v_exp_f32_e32 v183, v183
	v_exp_f32_e32 v184, v184
	v_exp_f32_e32 v185, v185
	v_exp_f32_e32 v186, v186
	v_exp_f32_e32 v187, v187
	v_exp_f32_e32 v188, v188
	v_exp_f32_e32 v189, v189
	v_add_u32_e32 v192, 0x42000, v190
	v_pk_add_f32 v[182:183], v[182:183], 1.0 op_sel_hi:[1,0]
	v_pk_add_f32 v[184:185], v[184:185], 1.0 op_sel_hi:[1,0]
	v_pk_add_f32 v[186:187], v[186:187], 1.0 op_sel_hi:[1,0]
	v_pk_add_f32 v[188:189], v[188:189], 1.0 op_sel_hi:[1,0]
	v_rcp_f32_e32 v182, v182
	v_rcp_f32_e32 v183, v183
	v_rcp_f32_e32 v184, v184
	v_rcp_f32_e32 v185, v185
	v_rcp_f32_e32 v186, v186
	v_rcp_f32_e32 v187, v187
	v_rcp_f32_e32 v188, v188
	v_rcp_f32_e32 v189, v189
	v_pk_mul_f32 v[76:77], v[76:77], v[156:157] op_sel_hi:[1,0]
	v_pk_mul_f32 v[78:79], v[78:79], v[156:157] op_sel_hi:[1,0]
	v_pk_mul_f32 v[68:69], v[68:69], v[156:157] op_sel_hi:[1,0]
	v_pk_mul_f32 v[70:71], v[70:71], v[156:157] op_sel_hi:[1,0]
	v_pk_mul_f32 v[80:81], v[80:81], v[182:183]
	v_pk_mul_f32 v[82:83], v[82:83], v[184:185]
	v_pk_mul_f32 v[72:73], v[72:73], v[186:187]
	v_pk_mul_f32 v[74:75], v[74:75], v[188:189]
	v_pk_mul_f32 v[76:77], v[76:77], v[80:81]
	v_pk_mul_f32 v[78:79], v[78:79], v[82:83]
	v_pk_mul_f32 v[68:69], v[68:69], v[72:73]
	v_pk_mul_f32 v[70:71], v[70:71], v[74:75]
	v_cvt_pk_bf16_f32 v76, v76, v77
	v_cvt_pk_bf16_f32 v77, v78, v79
	v_cvt_pk_bf16_f32 v68, v68, v69
	v_cvt_pk_bf16_f32 v69, v70, v71
	global_store_dwordx2 v192, v[76:77], s[30:31]
	global_store_dwordx2 v192, v[68:69], s[30:31] offset:128
	s_waitcnt lgkmcnt(3)
	v_pk_mul_f32 v[64:65], v[64:65], v[158:159] op_sel_hi:[1,0]
	v_pk_mul_f32 v[66:67], v[66:67], v[158:159] op_sel_hi:[1,0]
	v_pk_mul_f32 v[56:57], v[56:57], v[158:159] op_sel_hi:[1,0]
	v_pk_mul_f32 v[58:59], v[58:59], v[158:159] op_sel_hi:[1,0]
	v_pk_mul_f32 v[182:183], v[64:65], s[12:13] op_sel_hi:[1,0]
	v_pk_mul_f32 v[184:185], v[66:67], s[12:13] op_sel_hi:[1,0]
	v_pk_mul_f32 v[186:187], v[56:57], s[12:13] op_sel_hi:[1,0]
	v_pk_mul_f32 v[188:189], v[58:59], s[12:13] op_sel_hi:[1,0]
	v_exp_f32_e32 v182, v182
	v_exp_f32_e32 v183, v183
	v_exp_f32_e32 v184, v184
	v_exp_f32_e32 v185, v185
	v_exp_f32_e32 v186, v186
	v_exp_f32_e32 v187, v187
	v_exp_f32_e32 v188, v188
	v_exp_f32_e32 v189, v189
	v_add_u32_e32 v192, 0xb0000, v190
	v_pk_add_f32 v[182:183], v[182:183], 1.0 op_sel_hi:[1,0]
	v_pk_add_f32 v[184:185], v[184:185], 1.0 op_sel_hi:[1,0]
	v_pk_add_f32 v[186:187], v[186:187], 1.0 op_sel_hi:[1,0]
	v_pk_add_f32 v[188:189], v[188:189], 1.0 op_sel_hi:[1,0]
	v_rcp_f32_e32 v182, v182
	v_rcp_f32_e32 v183, v183
	v_rcp_f32_e32 v184, v184
	v_rcp_f32_e32 v185, v185
	v_rcp_f32_e32 v186, v186
	v_rcp_f32_e32 v187, v187
	v_rcp_f32_e32 v188, v188
	v_rcp_f32_e32 v189, v189
	v_pk_mul_f32 v[60:61], v[60:61], v[158:159] op_sel_hi:[1,0]
	v_pk_mul_f32 v[62:63], v[62:63], v[158:159] op_sel_hi:[1,0]
	v_pk_mul_f32 v[52:53], v[52:53], v[158:159] op_sel_hi:[1,0]
	v_pk_mul_f32 v[54:55], v[54:55], v[158:159] op_sel_hi:[1,0]
	v_pk_mul_f32 v[64:65], v[64:65], v[182:183]
	v_pk_mul_f32 v[66:67], v[66:67], v[184:185]
	v_pk_mul_f32 v[56:57], v[56:57], v[186:187]
	v_pk_mul_f32 v[58:59], v[58:59], v[188:189]
	v_pk_mul_f32 v[60:61], v[60:61], v[64:65]
	v_pk_mul_f32 v[62:63], v[62:63], v[66:67]
	v_pk_mul_f32 v[52:53], v[52:53], v[56:57]
	v_pk_mul_f32 v[54:55], v[54:55], v[58:59]
	v_cvt_pk_bf16_f32 v60, v60, v61
	v_cvt_pk_bf16_f32 v61, v62, v63
	v_cvt_pk_bf16_f32 v52, v52, v53
	v_cvt_pk_bf16_f32 v53, v54, v55
	global_store_dwordx2 v192, v[60:61], s[30:31]
	global_store_dwordx2 v192, v[52:53], s[30:31] offset:128
	s_waitcnt lgkmcnt(2)
; DI float fexp2(float x) { return __builtin_amdgcn_exp2f(x); }
;     ...
; #pragma unroll
;     for (int ai = 0; ai < 2; ++ai)
; #pragma unroll
;       for (int m = 0; m < 4; ++m) {
;         const int rowb = ai * 128 + wr * 64 + m * 16 + fq * 4;
;         const f32x4 rs4 = *(const f32x4*)(rstdL + rowb);
; #pragma unroll
;         for (int bj = 0; bj < 2; ++bj) {
;           bf16_t* op = e.out + (size_t)(m0 + rowb) * e.ldo + ((n0 + bj * 128 + wc * 32) >> 1) + fr;
; #pragma unroll
;           for (int j = 0; j < 4; ++j) {
;             const float g = acc[ai][bj][m][0][j] * rs4[j], u = acc[ai][bj][m][1][j] * rs4[j];
;             const float rv = g * __builtin_amdgcn_rcpf(1.f + fexp2(-g * LOG2E)) * u;
;             op[(size_t)j * e.ldo] = (bf16_t)(pack2(rv, 0.f) & 0xffffu);
;           }
;         }
;       }
;     __syncthreads();
	v_pk_mul_f32 v[48:49], v[48:49], v[160:161] op_sel_hi:[1,0]
	v_pk_mul_f32 v[50:51], v[50:51], v[160:161] op_sel_hi:[1,0]
	v_pk_mul_f32 v[40:41], v[40:41], v[160:161] op_sel_hi:[1,0]
	v_pk_mul_f32 v[42:43], v[42:43], v[160:161] op_sel_hi:[1,0]
	v_pk_mul_f32 v[182:183], v[48:49], s[12:13] op_sel_hi:[1,0]
	v_pk_mul_f32 v[184:185], v[50:51], s[12:13] op_sel_hi:[1,0]
	v_pk_mul_f32 v[186:187], v[40:41], s[12:13] op_sel_hi:[1,0]
	v_pk_mul_f32 v[188:189], v[42:43], s[12:13] op_sel_hi:[1,0]
	v_exp_f32_e32 v182, v182
	v_exp_f32_e32 v183, v183
	v_exp_f32_e32 v184, v184
	v_exp_f32_e32 v185, v185
	v_exp_f32_e32 v186, v186
	v_exp_f32_e32 v187, v187
	v_exp_f32_e32 v188, v188
	v_exp_f32_e32 v189, v189
	v_add_u32_e32 v192, 0xc6000, v190
	v_pk_add_f32 v[182:183], v[182:183], 1.0 op_sel_hi:[1,0]
	v_pk_add_f32 v[184:185], v[184:185], 1.0 op_sel_hi:[1,0]
	v_pk_add_f32 v[186:187], v[186:187], 1.0 op_sel_hi:[1,0]
	v_pk_add_f32 v[188:189], v[188:189], 1.0 op_sel_hi:[1,0]
	v_rcp_f32_e32 v182, v182
	v_rcp_f32_e32 v183, v183
	v_rcp_f32_e32 v184, v184
	v_rcp_f32_e32 v185, v185
	v_rcp_f32_e32 v186, v186
	v_rcp_f32_e32 v187, v187
	v_rcp_f32_e32 v188, v188
	v_rcp_f32_e32 v189, v189
	v_pk_mul_f32 v[44:45], v[44:45], v[160:161] op_sel_hi:[1,0]
	v_pk_mul_f32 v[46:47], v[46:47], v[160:161] op_sel_hi:[1,0]
	v_pk_mul_f32 v[36:37], v[36:37], v[160:161] op_sel_hi:[1,0]
	v_pk_mul_f32 v[38:39], v[38:39], v[160:161] op_sel_hi:[1,0]
	v_pk_mul_f32 v[48:49], v[48:49], v[182:183]
	v_pk_mul_f32 v[50:51], v[50:51], v[184:185]
	v_pk_mul_f32 v[40:41], v[40:41], v[186:187]
	v_pk_mul_f32 v[42:43], v[42:43], v[188:189]
	v_pk_mul_f32 v[44:45], v[44:45], v[48:49]
	v_pk_mul_f32 v[46:47], v[46:47], v[50:51]
	v_pk_mul_f32 v[36:37], v[36:37], v[40:41]
	v_pk_mul_f32 v[38:39], v[38:39], v[42:43]
	v_cvt_pk_bf16_f32 v44, v44, v45
	v_cvt_pk_bf16_f32 v45, v46, v47
	v_cvt_pk_bf16_f32 v36, v36, v37
	v_cvt_pk_bf16_f32 v37, v38, v39
	global_store_dwordx2 v192, v[44:45], s[30:31]
	global_store_dwordx2 v192, v[36:37], s[30:31] offset:128
	s_waitcnt lgkmcnt(1)
	v_pk_mul_f32 v[32:33], v[32:33], v[162:163] op_sel_hi:[1,0]
	v_pk_mul_f32 v[34:35], v[34:35], v[162:163] op_sel_hi:[1,0]
	v_pk_mul_f32 v[24:25], v[24:25], v[162:163] op_sel_hi:[1,0]
	v_pk_mul_f32 v[26:27], v[26:27], v[162:163] op_sel_hi:[1,0]
	v_pk_mul_f32 v[182:183], v[32:33], s[12:13] op_sel_hi:[1,0]
	v_pk_mul_f32 v[184:185], v[34:35], s[12:13] op_sel_hi:[1,0]
	v_pk_mul_f32 v[186:187], v[24:25], s[12:13] op_sel_hi:[1,0]
	v_pk_mul_f32 v[188:189], v[26:27], s[12:13] op_sel_hi:[1,0]
	v_exp_f32_e32 v182, v182
	v_exp_f32_e32 v183, v183
	v_exp_f32_e32 v184, v184
	v_exp_f32_e32 v185, v185
	v_exp_f32_e32 v186, v186
	v_exp_f32_e32 v187, v187
	v_exp_f32_e32 v188, v188
	v_exp_f32_e32 v189, v189
	v_add_u32_e32 v192, 0xdc000, v190
	v_pk_add_f32 v[182:183], v[182:183], 1.0 op_sel_hi:[1,0]
	v_pk_add_f32 v[184:185], v[184:185], 1.0 op_sel_hi:[1,0]
	v_pk_add_f32 v[186:187], v[186:187], 1.0 op_sel_hi:[1,0]
	v_pk_add_f32 v[188:189], v[188:189], 1.0 op_sel_hi:[1,0]
	v_rcp_f32_e32 v182, v182
	v_rcp_f32_e32 v183, v183
	v_rcp_f32_e32 v184, v184
	v_rcp_f32_e32 v185, v185
	v_rcp_f32_e32 v186, v186
	v_rcp_f32_e32 v187, v187
	v_rcp_f32_e32 v188, v188
	v_rcp_f32_e32 v189, v189
	v_pk_mul_f32 v[28:29], v[28:29], v[162:163] op_sel_hi:[1,0]
	v_pk_mul_f32 v[30:31], v[30:31], v[162:163] op_sel_hi:[1,0]
	v_pk_mul_f32 v[20:21], v[20:21], v[162:163] op_sel_hi:[1,0]
	v_pk_mul_f32 v[22:23], v[22:23], v[162:163] op_sel_hi:[1,0]
	v_pk_mul_f32 v[32:33], v[32:33], v[182:183]
	v_pk_mul_f32 v[34:35], v[34:35], v[184:185]
	v_pk_mul_f32 v[24:25], v[24:25], v[186:187]
	v_pk_mul_f32 v[26:27], v[26:27], v[188:189]
	v_pk_mul_f32 v[28:29], v[28:29], v[32:33]
	v_pk_mul_f32 v[30:31], v[30:31], v[34:35]
	v_pk_mul_f32 v[20:21], v[20:21], v[24:25]
	v_pk_mul_f32 v[22:23], v[22:23], v[26:27]
	v_cvt_pk_bf16_f32 v28, v28, v29
	v_cvt_pk_bf16_f32 v29, v30, v31
	v_cvt_pk_bf16_f32 v20, v20, v21
	v_cvt_pk_bf16_f32 v21, v22, v23
	global_store_dwordx2 v192, v[28:29], s[30:31]
	global_store_dwordx2 v192, v[20:21], s[30:31] offset:128
	s_waitcnt lgkmcnt(0)
	v_pk_mul_f32 v[16:17], v[16:17], v[164:165] op_sel_hi:[1,0]
	v_pk_mul_f32 v[18:19], v[18:19], v[164:165] op_sel_hi:[1,0]
	v_pk_mul_f32 v[8:9], v[8:9], v[164:165] op_sel_hi:[1,0]
	v_pk_mul_f32 v[10:11], v[10:11], v[164:165] op_sel_hi:[1,0]
	v_pk_mul_f32 v[182:183], v[16:17], s[12:13] op_sel_hi:[1,0]
	v_pk_mul_f32 v[184:185], v[18:19], s[12:13] op_sel_hi:[1,0]
	v_pk_mul_f32 v[186:187], v[8:9], s[12:13] op_sel_hi:[1,0]
	v_pk_mul_f32 v[188:189], v[10:11], s[12:13] op_sel_hi:[1,0]
	v_exp_f32_e32 v182, v182
	v_exp_f32_e32 v183, v183
	v_exp_f32_e32 v184, v184
	v_exp_f32_e32 v185, v185
	v_exp_f32_e32 v186, v186
	v_exp_f32_e32 v187, v187
	v_exp_f32_e32 v188, v188
	v_exp_f32_e32 v189, v189
	v_add_u32_e32 v192, 0xf2000, v190
	v_pk_add_f32 v[182:183], v[182:183], 1.0 op_sel_hi:[1,0]
	v_pk_add_f32 v[184:185], v[184:185], 1.0 op_sel_hi:[1,0]
	v_pk_add_f32 v[186:187], v[186:187], 1.0 op_sel_hi:[1,0]
	v_pk_add_f32 v[188:189], v[188:189], 1.0 op_sel_hi:[1,0]
	v_rcp_f32_e32 v182, v182
	v_rcp_f32_e32 v183, v183
	v_rcp_f32_e32 v184, v184
	v_rcp_f32_e32 v185, v185
	v_rcp_f32_e32 v186, v186
	v_rcp_f32_e32 v187, v187
	v_rcp_f32_e32 v188, v188
	v_rcp_f32_e32 v189, v189
	v_pk_mul_f32 v[12:13], v[12:13], v[164:165] op_sel_hi:[1,0]
	v_pk_mul_f32 v[14:15], v[14:15], v[164:165] op_sel_hi:[1,0]
	v_pk_mul_f32 v[4:5], v[4:5], v[164:165] op_sel_hi:[1,0]
	v_pk_mul_f32 v[6:7], v[6:7], v[164:165] op_sel_hi:[1,0]
	v_pk_mul_f32 v[16:17], v[16:17], v[182:183]
	v_pk_mul_f32 v[18:19], v[18:19], v[184:185]
	v_pk_mul_f32 v[8:9], v[8:9], v[186:187]
	v_pk_mul_f32 v[10:11], v[10:11], v[188:189]
	v_pk_mul_f32 v[12:13], v[12:13], v[16:17]
	v_pk_mul_f32 v[14:15], v[14:15], v[18:19]
	v_pk_mul_f32 v[4:5], v[4:5], v[8:9]
	v_pk_mul_f32 v[6:7], v[6:7], v[10:11]
	v_cvt_pk_bf16_f32 v12, v12, v13
	v_cvt_pk_bf16_f32 v13, v14, v15
	v_cvt_pk_bf16_f32 v4, v4, v5
	v_cvt_pk_bf16_f32 v5, v6, v7
	global_store_dwordx2 v192, v[12:13], s[30:31]
	global_store_dwordx2 v192, v[4:5], s[30:31] offset:128
	s_waitcnt vmcnt(63) expcnt(7) lgkmcnt(15)
	s_barrier

; #define LDA8(dst, b, h) _Pragma("unroll") for (int m = 0; m < 4; ++m) _Pragma("unroll") for (int k = 0; k < 2; ++k) \
;     dst[m][k] = *(const bf16x8*)((const char*)SA8(b, h) + lds_byte8(wr * 64 + m * 16 + fr, k * 32 + fq * 8))
; #define LDB8(dst, b, h) _Pragma("unroll") for (int n = 0; n < 2; ++n) _Pragma("unroll") for (int k = 0; k < 2; ++k) \
;     dst[n][k] = *(const bf16x8*)((const char*)SB8(b, h) + lds_byte8(wc * 32 + n * 16 + fr, k * 32 + fq * 8))
; #define WAIT_V8(n) asm volatile("s_waitcnt vmcnt(" #n ")" ::: "memory")
; #define WAIT_L8(n) asm volatile("s_waitcnt lgkmcnt(" #n ")" ::: "memory")
; #define BAR8 __builtin_amdgcn_s_barrier()
; #define SCHED8 __builtin_amdgcn_sched_barrier(0)
;     ...
;   for (int tt = 0; tt < nt - 2; tt += 2) {
;     LDB8(B0, 0, 0); SCHED8; LDA8(At, 0, 0); STAGE8(SA8(1, 1), A, lda, brow + 128, tt + 1);
;     WAIT_L8(8); BAR8; WAIT_L8(0); MMA8(0, 0, At, B0); BAR8; SCHED8;
;     LDB8(B1, 0, 1); STAGE8(SB8(0, 0), Bt, K, bcol, tt + 2);
;     BAR8; WAIT_L8(0); MMA8(0, 1, At, B1); BAR8;
;     LDA8(At, 0, 1); STAGE8(SA8(0, 0), A, lda, brow, tt + 2);
;     BAR8; WAIT_L8(0); MMA8(1, 0, At, B0); BAR8; SCHED8;
;     STAGE8(SB8(0, 1), Bt, K, bcol + 128, tt + 2);
;     WAIT_V8(6); BAR8; MMA8(1, 1, At, B1); BAR8;
;     LDB8(B0, 1, 0); SCHED8; LDA8(At, 1, 0); STAGE8(SA8(0, 1), A, lda, brow + 128, tt + 2);
;     WAIT_L8(8); BAR8; WAIT_L8(0); MMA8(0, 0, At, B0); BAR8; SCHED8;
;     LDB8(B1, 1, 1); STAGE8(SB8(1, 0), Bt, K, bcol, tt + 3);
;     BAR8; WAIT_L8(0); MMA8(0, 1, At, B1); BAR8;
;     LDA8(At, 1, 1); STAGE8(SA8(1, 0), A, lda, brow, tt + 3);
;     BAR8; WAIT_L8(0); MMA8(1, 0, At, B0); BAR8; SCHED8;
;     STAGE8(SB8(1, 1), Bt, K, bcol + 128, tt + 3);
;     WAIT_V8(6); BAR8; MMA8(1, 1, At, B1); BAR8;
;   }
.LBB0_1259:
	ds_read_b128 v[174:177], v171
	ds_read_b128 v[178:181], v171 offset:1024
	ds_read_b128 v[182:185], v171 offset:2048
	ds_read_b128 v[186:189], v171 offset:3072
	v_add_u32_e32 v172, 0xc000, v150
	v_lshl_add_u64 v[222:223], v[138:139], 0, s[12:13]
	v_readfirstlane_b32 s14, v172
	v_add_u32_e32 v173, 0xe000, v150
	v_lshl_add_u64 v[226:227], v[222:223], 0, s[34:35]
	s_mov_b32 m0, s14
	v_lshl_add_u64 v[236:237], v[140:141], 0, s[12:13]
	v_readfirstlane_b32 s14, v173
	ds_read_b128 v[190:193], v161
	ds_read_b128 v[194:197], v161 offset:1024
	ds_read_b128 v[198:201], v160
	ds_read_b128 v[202:205], v160 offset:1024
	ds_read_b128 v[206:209], v159
	ds_read_b128 v[210:213], v159 offset:1024
	ds_read_b128 v[214:217], v158
	ds_read_b128 v[218:221], v158 offset:1024
	global_load_lds_dwordx4 v[226:227], off
	v_lshl_add_u64 v[226:227], v[236:237], 0, s[34:35]
	s_mov_b32 m0, s14
	s_nop 0
	global_load_lds_dwordx4 v[226:227], off
	s_waitcnt lgkmcnt(8)
	s_barrier
	s_waitcnt lgkmcnt(0)
	s_setprio 1
	s_waitcnt lgkmcnt(0)
	v_mfma_f32_16x16x32_f16 v[128:131], v[174:177], v[190:193], v[128:131]
	v_mfma_f32_16x16x32_f16 v[124:127], v[182:185], v[190:193], v[124:127]
	v_mfma_f32_16x16x32_f16 v[120:123], v[174:177], v[198:201], v[120:123]
	v_mfma_f32_16x16x32_f16 v[116:119], v[182:185], v[198:201], v[116:119]
	v_mfma_f32_16x16x32_f16 v[112:115], v[174:177], v[206:209], v[112:115]
	v_mfma_f32_16x16x32_f16 v[108:111], v[182:185], v[206:209], v[108:111]
	v_mfma_f32_16x16x32_f16 v[104:107], v[174:177], v[214:217], v[104:107]
	v_mfma_f32_16x16x32_f16 v[100:103], v[182:185], v[214:217], v[100:103]
	v_mfma_f32_16x16x32_f16 v[128:131], v[178:181], v[194:197], v[128:131]
	v_mfma_f32_16x16x32_f16 v[124:127], v[186:189], v[194:197], v[124:127]
	v_mfma_f32_16x16x32_f16 v[120:123], v[178:181], v[202:205], v[120:123]
	v_mfma_f32_16x16x32_f16 v[116:119], v[186:189], v[202:205], v[116:119]
	v_mfma_f32_16x16x32_f16 v[112:115], v[178:181], v[210:213], v[112:115]
	v_mfma_f32_16x16x32_f16 v[108:111], v[186:189], v[210:213], v[108:111]
	v_mfma_f32_16x16x32_f16 v[104:107], v[178:181], v[218:221], v[104:107]
	v_mfma_f32_16x16x32_f16 v[100:103], v[186:189], v[218:221], v[100:103]
	s_setprio 0
	s_barrier
	v_lshl_add_u64 v[246:247], v[142:143], 0, s[12:13]
	v_readfirstlane_b32 s14, v151
	v_lshl_add_u64 v[248:249], v[246:247], 0, s[36:37]
	s_mov_b32 m0, s14
	ds_read_b128 v[226:229], v169
	ds_read_b128 v[230:233], v169 offset:1024
	ds_read_b128 v[238:241], v169 offset:2048
	ds_read_b128 v[242:245], v169 offset:3072
	global_load_lds_dwordx4 v[248:249], off
	v_lshl_add_u64 v[248:249], v[144:145], 0, s[12:13]
	v_readfirstlane_b32 s14, v153
	v_lshl_add_u64 v[250:251], v[248:249], 0, s[36:37]
	s_mov_b32 m0, s14
	s_nop 0
	global_load_lds_dwordx4 v[250:251], off
	s_barrier
	s_waitcnt lgkmcnt(0)
	s_setprio 1
	s_waitcnt lgkmcnt(0)
	v_mfma_f32_16x16x32_f16 v[96:99], v[226:229], v[190:193], v[96:99]
	v_mfma_f32_16x16x32_f16 v[92:95], v[238:241], v[190:193], v[92:95]
	v_mfma_f32_16x16x32_f16 v[88:91], v[226:229], v[198:201], v[88:91]
	v_mfma_f32_16x16x32_f16 v[84:87], v[238:241], v[198:201], v[84:87]
	v_mfma_f32_16x16x32_f16 v[80:83], v[226:229], v[206:209], v[80:83]
	v_mfma_f32_16x16x32_f16 v[76:79], v[238:241], v[206:209], v[76:79]
	v_mfma_f32_16x16x32_f16 v[72:75], v[226:229], v[214:217], v[72:75]
	v_mfma_f32_16x16x32_f16 v[68:71], v[238:241], v[214:217], v[68:71]
	v_mfma_f32_16x16x32_f16 v[96:99], v[230:233], v[194:197], v[96:99]
	v_mfma_f32_16x16x32_f16 v[92:95], v[242:245], v[194:197], v[92:95]
	v_mfma_f32_16x16x32_f16 v[88:91], v[230:233], v[202:205], v[88:91]
	v_mfma_f32_16x16x32_f16 v[84:87], v[242:245], v[202:205], v[84:87]
	v_mfma_f32_16x16x32_f16 v[80:83], v[230:233], v[210:213], v[80:83]
	v_mfma_f32_16x16x32_f16 v[76:79], v[242:245], v[210:213], v[76:79]
	v_mfma_f32_16x16x32_f16 v[72:75], v[230:233], v[218:221], v[72:75]
	v_mfma_f32_16x16x32_f16 v[68:71], v[242:245], v[218:221], v[68:71]
	s_setprio 0
	v_readfirstlane_b32 s14, v150
	v_lshl_add_u64 v[250:251], v[222:223], 0, s[10:11]
	s_mov_b32 m0, s14
	v_readfirstlane_b32 s14, v152
	s_barrier
	ds_read_b128 v[190:193], v161 offset:16384
	ds_read_b128 v[194:197], v161 offset:17408
	ds_read_b128 v[198:201], v160 offset:16384
	ds_read_b128 v[202:205], v160 offset:17408
	ds_read_b128 v[206:209], v159 offset:16384
	ds_read_b128 v[210:213], v159 offset:17408
	ds_read_b128 v[214:217], v158 offset:16384
	ds_read_b128 v[218:221], v158 offset:17408
	global_load_lds_dwordx4 v[250:251], off
	v_lshl_add_u64 v[250:251], v[236:237], 0, s[10:11]
	s_mov_b32 m0, s14
	s_nop 0
	global_load_lds_dwordx4 v[250:251], off
	s_barrier
	s_waitcnt lgkmcnt(0)
	s_setprio 1
	s_waitcnt lgkmcnt(0)
	v_mfma_f32_16x16x32_f16 v[64:67], v[174:177], v[190:193], v[64:67]
	v_mfma_f32_16x16x32_f16 v[60:63], v[182:185], v[190:193], v[60:63]
	v_mfma_f32_16x16x32_f16 v[56:59], v[174:177], v[198:201], v[56:59]
	v_mfma_f32_16x16x32_f16 v[52:55], v[182:185], v[198:201], v[52:55]
	v_mfma_f32_16x16x32_f16 v[48:51], v[174:177], v[206:209], v[48:51]
	v_mfma_f32_16x16x32_f16 v[44:47], v[182:185], v[206:209], v[44:47]
	v_mfma_f32_16x16x32_f16 v[40:43], v[174:177], v[214:217], v[40:43]
	v_mfma_f32_16x16x32_f16 v[36:39], v[182:185], v[214:217], v[36:39]
	v_mfma_f32_16x16x32_f16 v[64:67], v[178:181], v[194:197], v[64:67]
	v_mfma_f32_16x16x32_f16 v[60:63], v[186:189], v[194:197], v[60:63]
	v_mfma_f32_16x16x32_f16 v[56:59], v[178:181], v[202:205], v[56:59]
	v_mfma_f32_16x16x32_f16 v[52:55], v[186:189], v[202:205], v[52:55]
	v_mfma_f32_16x16x32_f16 v[48:51], v[178:181], v[210:213], v[48:51]
	v_mfma_f32_16x16x32_f16 v[44:47], v[186:189], v[210:213], v[44:47]
	v_mfma_f32_16x16x32_f16 v[40:43], v[178:181], v[218:221], v[40:43]
	v_mfma_f32_16x16x32_f16 v[36:39], v[186:189], v[218:221], v[36:39]
	s_setprio 0
	s_barrier
; #define LDA8(dst, b, h) _Pragma("unroll") for (int m = 0; m < 4; ++m) _Pragma("unroll") for (int k = 0; k < 2; ++k) \
;     dst[m][k] = *(const bf16x8*)((const char*)SA8(b, h) + lds_byte8(wr * 64 + m * 16 + fr, k * 32 + fq * 8))
; #define LDB8(dst, b, h) _Pragma("unroll") for (int n = 0; n < 2; ++n) _Pragma("unroll") for (int k = 0; k < 2; ++k) \
;     dst[n][k] = *(const bf16x8*)((const char*)SB8(b, h) + lds_byte8(wc * 32 + n * 16 + fr, k * 32 + fq * 8))
; #define WAIT_V8(n) asm volatile("s_waitcnt vmcnt(" #n ")" ::: "memory")
; #define WAIT_L8(n) asm volatile("s_waitcnt lgkmcnt(" #n ")" ::: "memory")
; #define BAR8 __builtin_amdgcn_s_barrier()
; #define SCHED8 __builtin_amdgcn_sched_barrier(0)
;     ...
;   for (int tt = 0; tt < nt - 2; tt += 2) {
;     LDB8(B0, 0, 0); SCHED8; LDA8(At, 0, 0); STAGE8(SA8(1, 1), A, lda, brow + 128, tt + 1);
;     WAIT_L8(8); BAR8; WAIT_L8(0); MMA8(0, 0, At, B0); BAR8; SCHED8;
;     LDB8(B1, 0, 1); STAGE8(SB8(0, 0), Bt, K, bcol, tt + 2);
;     BAR8; WAIT_L8(0); MMA8(0, 1, At, B1); BAR8;
;     LDA8(At, 0, 1); STAGE8(SA8(0, 0), A, lda, brow, tt + 2);
;     BAR8; WAIT_L8(0); MMA8(1, 0, At, B0); BAR8; SCHED8;
;     STAGE8(SB8(0, 1), Bt, K, bcol + 128, tt + 2);
;     WAIT_V8(6); BAR8; MMA8(1, 1, At, B1); BAR8;
;     LDB8(B0, 1, 0); SCHED8; LDA8(At, 1, 0); STAGE8(SA8(0, 1), A, lda, brow + 128, tt + 2);
;     WAIT_L8(8); BAR8; WAIT_L8(0); MMA8(0, 0, At, B0); BAR8; SCHED8;
;     LDB8(B1, 1, 1); STAGE8(SB8(1, 0), Bt, K, bcol, tt + 3);
;     BAR8; WAIT_L8(0); MMA8(0, 1, At, B1); BAR8;
;     LDA8(At, 1, 1); STAGE8(SA8(1, 0), A, lda, brow, tt + 3);
;     BAR8; WAIT_L8(0); MMA8(1, 0, At, B0); BAR8; SCHED8;
;     STAGE8(SB8(1, 1), Bt, K, bcol + 128, tt + 3);
;     WAIT_V8(6); BAR8; MMA8(1, 1, At, B1); BAR8;
;   }
	v_readfirstlane_b32 s14, v154
	v_lshl_add_u64 v[174:175], v[246:247], 0, s[40:41]
	s_mov_b32 m0, s14
	v_readfirstlane_b32 s14, v155
	global_load_lds_dwordx4 v[174:175], off
	v_lshl_add_u64 v[174:175], v[248:249], 0, s[40:41]
	s_mov_b32 m0, s14
	s_nop 0
	global_load_lds_dwordx4 v[174:175], off
	s_waitcnt vmcnt(6)
	s_barrier
	s_setprio 1
	v_mfma_f32_16x16x32_f16 v[32:35], v[226:229], v[190:193], v[32:35]
	v_mfma_f32_16x16x32_f16 v[28:31], v[238:241], v[190:193], v[28:31]
	v_mfma_f32_16x16x32_f16 v[24:27], v[226:229], v[198:201], v[24:27]
	v_mfma_f32_16x16x32_f16 v[20:23], v[238:241], v[198:201], v[20:23]
	v_mfma_f32_16x16x32_f16 v[16:19], v[226:229], v[206:209], v[16:19]
	v_mfma_f32_16x16x32_f16 v[12:15], v[238:241], v[206:209], v[12:15]
	v_mfma_f32_16x16x32_f16 v[8:11], v[226:229], v[214:217], v[8:11]
	v_mfma_f32_16x16x32_f16 v[4:7], v[238:241], v[214:217], v[4:7]
	v_mfma_f32_16x16x32_f16 v[32:35], v[230:233], v[194:197], v[32:35]
	v_mfma_f32_16x16x32_f16 v[28:31], v[242:245], v[194:197], v[28:31]
	v_mfma_f32_16x16x32_f16 v[24:27], v[230:233], v[202:205], v[24:27]
	v_mfma_f32_16x16x32_f16 v[20:23], v[242:245], v[202:205], v[20:23]
	v_mfma_f32_16x16x32_f16 v[16:19], v[230:233], v[210:213], v[16:19]
	v_mfma_f32_16x16x32_f16 v[12:15], v[242:245], v[210:213], v[12:15]
	v_mfma_f32_16x16x32_f16 v[8:11], v[230:233], v[218:221], v[8:11]
	v_mfma_f32_16x16x32_f16 v[4:7], v[242:245], v[218:221], v[4:7]
	s_setprio 0
	s_barrier
	ds_read_b128 v[174:177], v163
	ds_read_b128 v[178:181], v163 offset:1024
	ds_read_b128 v[182:185], v163 offset:2048
	ds_read_b128 v[186:189], v163 offset:3072
	v_readfirstlane_b32 s14, v156
	v_lshl_add_u64 v[226:227], v[222:223], 0, s[18:19]
	s_mov_b32 m0, s14
	v_readfirstlane_b32 s14, v157
	ds_read_b128 v[190:193], v161 offset:32768
	ds_read_b128 v[194:197], v161 offset:33792
	ds_read_b128 v[198:201], v160 offset:32768
	ds_read_b128 v[202:205], v160 offset:33792
	ds_read_b128 v[206:209], v159 offset:32768
	ds_read_b128 v[210:213], v159 offset:33792
	ds_read_b128 v[214:217], v158 offset:32768
	ds_read_b128 v[218:221], v158 offset:33792
	global_load_lds_dwordx4 v[226:227], off
	v_lshl_add_u64 v[226:227], v[236:237], 0, s[18:19]
	s_mov_b32 m0, s14
	s_nop 0
	global_load_lds_dwordx4 v[226:227], off
	s_waitcnt lgkmcnt(8)
	s_barrier
	s_waitcnt lgkmcnt(0)
	s_setprio 1
	s_waitcnt lgkmcnt(0)
	v_mfma_f32_16x16x32_f16 v[128:131], v[174:177], v[190:193], v[128:131]
	v_mfma_f32_16x16x32_f16 v[124:127], v[182:185], v[190:193], v[124:127]
	v_mfma_f32_16x16x32_f16 v[120:123], v[174:177], v[198:201], v[120:123]
	v_mfma_f32_16x16x32_f16 v[116:119], v[182:185], v[198:201], v[116:119]
	v_mfma_f32_16x16x32_f16 v[112:115], v[174:177], v[206:209], v[112:115]
	v_mfma_f32_16x16x32_f16 v[108:111], v[182:185], v[206:209], v[108:111]
	v_mfma_f32_16x16x32_f16 v[104:107], v[174:177], v[214:217], v[104:107]
	v_mfma_f32_16x16x32_f16 v[100:103], v[182:185], v[214:217], v[100:103]
	v_mfma_f32_16x16x32_f16 v[128:131], v[178:181], v[194:197], v[128:131]
	v_mfma_f32_16x16x32_f16 v[124:127], v[186:189], v[194:197], v[124:127]
	v_mfma_f32_16x16x32_f16 v[120:123], v[178:181], v[202:205], v[120:123]
	v_mfma_f32_16x16x32_f16 v[116:119], v[186:189], v[202:205], v[116:119]
	v_mfma_f32_16x16x32_f16 v[112:115], v[178:181], v[210:213], v[112:115]
	v_mfma_f32_16x16x32_f16 v[108:111], v[186:189], v[210:213], v[108:111]
	v_mfma_f32_16x16x32_f16 v[104:107], v[178:181], v[218:221], v[104:107]
	v_mfma_f32_16x16x32_f16 v[100:103], v[186:189], v[218:221], v[100:103]
	s_setprio 0
	s_barrier
	v_readfirstlane_b32 s14, v164
	v_lshl_add_u64 v[250:251], v[246:247], 0, s[42:43]
	s_mov_b32 m0, s14
	v_readfirstlane_b32 s14, v165
	ds_read_b128 v[226:229], v162
	ds_read_b128 v[230:233], v162 offset:1024
	ds_read_b128 v[238:241], v162 offset:2048
	ds_read_b128 v[242:245], v162 offset:3072
	global_load_lds_dwordx4 v[250:251], off
	v_lshl_add_u64 v[250:251], v[248:249], 0, s[42:43]
	s_mov_b32 m0, s14
	s_nop 0
	global_load_lds_dwordx4 v[250:251], off
	s_barrier
	s_waitcnt lgkmcnt(0)
	s_setprio 1
	s_waitcnt lgkmcnt(0)
	v_mfma_f32_16x16x32_f16 v[96:99], v[226:229], v[190:193], v[96:99]
	v_mfma_f32_16x16x32_f16 v[92:95], v[238:241], v[190:193], v[92:95]
	v_mfma_f32_16x16x32_f16 v[88:91], v[226:229], v[198:201], v[88:91]
	v_mfma_f32_16x16x32_f16 v[84:87], v[238:241], v[198:201], v[84:87]
	v_mfma_f32_16x16x32_f16 v[80:83], v[226:229], v[206:209], v[80:83]
	v_mfma_f32_16x16x32_f16 v[76:79], v[238:241], v[206:209], v[76:79]
	v_mfma_f32_16x16x32_f16 v[72:75], v[226:229], v[214:217], v[72:75]
	v_mfma_f32_16x16x32_f16 v[68:71], v[238:241], v[214:217], v[68:71]
	v_mfma_f32_16x16x32_f16 v[96:99], v[230:233], v[194:197], v[96:99]
	v_mfma_f32_16x16x32_f16 v[92:95], v[242:245], v[194:197], v[92:95]
	v_mfma_f32_16x16x32_f16 v[88:91], v[230:233], v[202:205], v[88:91]
	v_mfma_f32_16x16x32_f16 v[84:87], v[242:245], v[202:205], v[84:87]
	v_mfma_f32_16x16x32_f16 v[80:83], v[230:233], v[210:213], v[80:83]
	v_mfma_f32_16x16x32_f16 v[76:79], v[242:245], v[210:213], v[76:79]
	v_mfma_f32_16x16x32_f16 v[72:75], v[230:233], v[218:221], v[72:75]
	v_mfma_f32_16x16x32_f16 v[68:71], v[242:245], v[218:221], v[68:71]
	s_setprio 0
	v_readfirstlane_b32 s14, v166
	v_lshl_add_u64 v[222:223], v[222:223], 0, s[22:23]
	s_mov_b32 m0, s14
	v_readfirstlane_b32 s14, v167
	s_barrier
	ds_read_b128 v[190:193], v161 offset:49152
	ds_read_b128 v[194:197], v161 offset:50176
	ds_read_b128 v[198:201], v160 offset:49152
	ds_read_b128 v[202:205], v160 offset:50176
	ds_read_b128 v[206:209], v159 offset:49152
	ds_read_b128 v[210:213], v159 offset:50176
	ds_read_b128 v[214:217], v158 offset:49152
	ds_read_b128 v[218:221], v158 offset:50176
	global_load_lds_dwordx4 v[222:223], off
	v_lshl_add_u64 v[222:223], v[236:237], 0, s[22:23]
	s_mov_b32 m0, s14
	s_nop 0
	global_load_lds_dwordx4 v[222:223], off
	s_barrier
; #define LDA8(dst, b, h) _Pragma("unroll") for (int m = 0; m < 4; ++m) _Pragma("unroll") for (int k = 0; k < 2; ++k) \
;     dst[m][k] = *(const bf16x8*)((const char*)SA8(b, h) + lds_byte8(wr * 64 + m * 16 + fr, k * 32 + fq * 8))
; #define LDB8(dst, b, h) _Pragma("unroll") for (int n = 0; n < 2; ++n) _Pragma("unroll") for (int k = 0; k < 2; ++k) \
;     dst[n][k] = *(const bf16x8*)((const char*)SB8(b, h) + lds_byte8(wc * 32 + n * 16 + fr, k * 32 + fq * 8))
; #define WAIT_V8(n) asm volatile("s_waitcnt vmcnt(" #n ")" ::: "memory")
; #define WAIT_L8(n) asm volatile("s_waitcnt lgkmcnt(" #n ")" ::: "memory")
; #define BAR8 __builtin_amdgcn_s_barrier()
; #define SCHED8 __builtin_amdgcn_sched_barrier(0)
;     ...
;   for (int tt = 0; tt < nt - 2; tt += 2) {
;     LDB8(B0, 0, 0); SCHED8; LDA8(At, 0, 0); STAGE8(SA8(1, 1), A, lda, brow + 128, tt + 1);
;     WAIT_L8(8); BAR8; WAIT_L8(0); MMA8(0, 0, At, B0); BAR8; SCHED8;
;     LDB8(B1, 0, 1); STAGE8(SB8(0, 0), Bt, K, bcol, tt + 2);
;     BAR8; WAIT_L8(0); MMA8(0, 1, At, B1); BAR8;
;     LDA8(At, 0, 1); STAGE8(SA8(0, 0), A, lda, brow, tt + 2);
;     BAR8; WAIT_L8(0); MMA8(1, 0, At, B0); BAR8; SCHED8;
;     STAGE8(SB8(0, 1), Bt, K, bcol + 128, tt + 2);
;     WAIT_V8(6); BAR8; MMA8(1, 1, At, B1); BAR8;
;     LDB8(B0, 1, 0); SCHED8; LDA8(At, 1, 0); STAGE8(SA8(0, 1), A, lda, brow + 128, tt + 2);
;     WAIT_L8(8); BAR8; WAIT_L8(0); MMA8(0, 0, At, B0); BAR8; SCHED8;
;     LDB8(B1, 1, 1); STAGE8(SB8(1, 0), Bt, K, bcol, tt + 3);
;     BAR8; WAIT_L8(0); MMA8(0, 1, At, B1); BAR8;
;     LDA8(At, 1, 1); STAGE8(SA8(1, 0), A, lda, brow, tt + 3);
;     BAR8; WAIT_L8(0); MMA8(1, 0, At, B0); BAR8; SCHED8;
;     STAGE8(SB8(1, 1), Bt, K, bcol + 128, tt + 3);
;     WAIT_V8(6); BAR8; MMA8(1, 1, At, B1); BAR8;
;   }
;   { LDB8(B0, 0, 0); LDA8(At, 0, 0); STAGE8(SA8(1, 1), A, lda, brow + 128, nt - 1);
;     BAR8; WAIT_L8(0); MMA8(0, 0, At, B0); BAR8;
;     LDB8(B1, 0, 1); BAR8; WAIT_L8(0); MMA8(0, 1, At, B1); BAR8;
;     LDA8(At, 0, 1); WAIT_V8(4); BAR8; WAIT_L8(0); MMA8(1, 0, At, B0); MMA8(1, 1, At, B1); BAR8; }
	s_waitcnt lgkmcnt(0)
	s_setprio 1
	s_waitcnt lgkmcnt(0)
	v_mfma_f32_16x16x32_f16 v[64:67], v[174:177], v[190:193], v[64:67]
	v_mfma_f32_16x16x32_f16 v[60:63], v[182:185], v[190:193], v[60:63]
	v_mfma_f32_16x16x32_f16 v[56:59], v[174:177], v[198:201], v[56:59]
	v_mfma_f32_16x16x32_f16 v[52:55], v[182:185], v[198:201], v[52:55]
	v_mfma_f32_16x16x32_f16 v[48:51], v[174:177], v[206:209], v[48:51]
	v_mfma_f32_16x16x32_f16 v[44:47], v[182:185], v[206:209], v[44:47]
	v_mfma_f32_16x16x32_f16 v[40:43], v[174:177], v[214:217], v[40:43]
	v_mfma_f32_16x16x32_f16 v[36:39], v[182:185], v[214:217], v[36:39]
	v_mfma_f32_16x16x32_f16 v[64:67], v[178:181], v[194:197], v[64:67]
	v_mfma_f32_16x16x32_f16 v[60:63], v[186:189], v[194:197], v[60:63]
	v_mfma_f32_16x16x32_f16 v[56:59], v[178:181], v[202:205], v[56:59]
	v_mfma_f32_16x16x32_f16 v[52:55], v[186:189], v[202:205], v[52:55]
	v_mfma_f32_16x16x32_f16 v[48:51], v[178:181], v[210:213], v[48:51]
	v_mfma_f32_16x16x32_f16 v[44:47], v[186:189], v[210:213], v[44:47]
	v_mfma_f32_16x16x32_f16 v[40:43], v[178:181], v[218:221], v[40:43]
	v_mfma_f32_16x16x32_f16 v[36:39], v[186:189], v[218:221], v[36:39]
	s_setprio 0
	s_barrier
	v_readfirstlane_b32 s14, v168
	v_lshl_add_u64 v[174:175], v[246:247], 0, s[44:45]
	s_mov_b32 m0, s14
	v_readfirstlane_b32 s14, v170
	global_load_lds_dwordx4 v[174:175], off
	v_lshl_add_u64 v[174:175], v[248:249], 0, s[44:45]
	s_mov_b32 m0, s14
	s_nop 0
	global_load_lds_dwordx4 v[174:175], off
	s_waitcnt vmcnt(6)
	s_barrier
	s_setprio 1
	v_mfma_f32_16x16x32_f16 v[32:35], v[226:229], v[190:193], v[32:35]
	v_mfma_f32_16x16x32_f16 v[28:31], v[238:241], v[190:193], v[28:31]
	v_mfma_f32_16x16x32_f16 v[24:27], v[226:229], v[198:201], v[24:27]
	v_mfma_f32_16x16x32_f16 v[20:23], v[238:241], v[198:201], v[20:23]
	v_mfma_f32_16x16x32_f16 v[16:19], v[226:229], v[206:209], v[16:19]
	v_mfma_f32_16x16x32_f16 v[12:15], v[238:241], v[206:209], v[12:15]
	v_mfma_f32_16x16x32_f16 v[8:11], v[226:229], v[214:217], v[8:11]
	v_mfma_f32_16x16x32_f16 v[4:7], v[238:241], v[214:217], v[4:7]
	v_mfma_f32_16x16x32_f16 v[32:35], v[230:233], v[194:197], v[32:35]
	v_mfma_f32_16x16x32_f16 v[28:31], v[242:245], v[194:197], v[28:31]
	v_mfma_f32_16x16x32_f16 v[24:27], v[230:233], v[202:205], v[24:27]
	v_mfma_f32_16x16x32_f16 v[20:23], v[242:245], v[202:205], v[20:23]
	v_mfma_f32_16x16x32_f16 v[16:19], v[230:233], v[210:213], v[16:19]
	v_mfma_f32_16x16x32_f16 v[12:15], v[242:245], v[210:213], v[12:15]
	v_mfma_f32_16x16x32_f16 v[8:11], v[230:233], v[218:221], v[8:11]
	v_mfma_f32_16x16x32_f16 v[4:7], v[242:245], v[218:221], v[4:7]
	s_setprio 0
	s_add_i32 s1, s1, 2
	s_add_u32 s12, s12, 0x100
	s_addc_u32 s13, s13, 0
	s_cmp_lt_u32 s1, 12
	s_barrier
	s_cbranch_scc1 .LBB0_1259
	s_add_u32 s8, s8, 0x40780
	s_addc_u32 s9, s9, 0
	v_lshl_add_u64 v[132:133], s[8:9], 0, v[132:133]
	v_readfirstlane_b32 s1, v172
	v_lshl_add_u64 v[0:1], v[0:1], 1, v[132:133]
	s_mov_b32 m0, s1
	ds_read_b128 v[138:141], v171
	ds_read_b128 v[142:145], v171 offset:1024
	ds_read_b128 v[150:153], v171 offset:2048
	ds_read_b128 v[154:157], v171 offset:3072
	ds_read_b128 v[164:167], v161
	ds_read_b128 v[174:177], v161 offset:1024
	ds_read_b128 v[178:181], v160
	ds_read_b128 v[182:185], v160 offset:1024
	ds_read_b128 v[186:189], v159
	ds_read_b128 v[190:193], v159 offset:1024
	ds_read_b128 v[194:197], v158
	ds_read_b128 v[198:201], v158 offset:1024
	global_load_lds_dwordx4 v[0:1], off
	v_lshl_add_u64 v[0:1], s[8:9], 0, v[136:137]
	v_readfirstlane_b32 s1, v173
	v_lshl_add_u64 v[0:1], v[134:135], 1, v[0:1]
	s_mov_b32 m0, s1
	s_nop 0
	global_load_lds_dwordx4 v[0:1], off
	s_barrier
	s_waitcnt lgkmcnt(0)
	s_setprio 1
	s_waitcnt lgkmcnt(0)
	v_mfma_f32_16x16x32_f16 v[128:131], v[138:141], v[164:167], v[128:131]
	v_mfma_f32_16x16x32_f16 v[124:127], v[150:153], v[164:167], v[124:127]
	v_mfma_f32_16x16x32_f16 v[120:123], v[138:141], v[178:181], v[120:123]
	v_mfma_f32_16x16x32_f16 v[116:119], v[150:153], v[178:181], v[116:119]
	v_mfma_f32_16x16x32_f16 v[104:107], v[138:141], v[194:197], v[104:107]
	v_mfma_f32_16x16x32_f16 v[100:103], v[150:153], v[194:197], v[100:103]
	v_mfma_f32_16x16x32_f16 v[128:131], v[142:145], v[174:177], v[128:131]
	v_mfma_f32_16x16x32_f16 v[124:127], v[154:157], v[174:177], v[124:127]
	v_mfma_f32_16x16x32_f16 v[120:123], v[142:145], v[182:185], v[120:123]
	v_mfma_f32_16x16x32_f16 v[116:119], v[154:157], v[182:185], v[116:119]
	v_mfma_f32_16x16x32_f16 v[112:115], v[138:141], v[186:189], v[112:115]
	v_mfma_f32_16x16x32_f16 v[108:111], v[150:153], v[186:189], v[108:111]
	v_mfma_f32_16x16x32_f16 v[104:107], v[142:145], v[198:201], v[104:107]
	v_mfma_f32_16x16x32_f16 v[100:103], v[154:157], v[198:201], v[100:103]
	v_mfma_f32_16x16x32_f16 v[132:135], v[142:145], v[190:193], v[112:115]
	v_mfma_f32_16x16x32_f16 v[170:173], v[154:157], v[190:193], v[108:111]
	s_setprio 0
	s_barrier
	s_nop 1
	ds_read_b128 v[108:111], v169
	ds_read_b128 v[112:115], v169 offset:1024
	ds_read_b128 v[202:205], v169 offset:2048
	ds_read_b128 v[206:209], v169 offset:3072
	s_barrier
	s_waitcnt lgkmcnt(0)
	s_setprio 1
	s_waitcnt lgkmcnt(0)
	v_mfma_f32_16x16x32_f16 v[88:91], v[108:111], v[178:181], v[88:91]
	v_mfma_f32_16x16x32_f16 v[84:87], v[202:205], v[178:181], v[84:87]
	v_mfma_f32_16x16x32_f16 v[72:75], v[108:111], v[194:197], v[72:75]
	v_mfma_f32_16x16x32_f16 v[68:71], v[202:205], v[194:197], v[68:71]
	v_mfma_f32_16x16x32_f16 v[96:99], v[108:111], v[164:167], v[96:99]
	v_mfma_f32_16x16x32_f16 v[92:95], v[202:205], v[164:167], v[92:95]
	v_mfma_f32_16x16x32_f16 v[88:91], v[112:115], v[182:185], v[88:91]
	v_mfma_f32_16x16x32_f16 v[84:87], v[206:209], v[182:185], v[84:87]
	v_mfma_f32_16x16x32_f16 v[80:83], v[108:111], v[186:189], v[80:83]
	v_mfma_f32_16x16x32_f16 v[76:79], v[202:205], v[186:189], v[76:79]
	v_mfma_f32_16x16x32_f16 v[72:75], v[112:115], v[198:201], v[72:75]
	v_mfma_f32_16x16x32_f16 v[68:71], v[206:209], v[198:201], v[68:71]
	v_mfma_f32_16x16x32_f16 v[210:213], v[112:115], v[174:177], v[96:99]
	v_mfma_f32_16x16x32_f16 v[164:167], v[206:209], v[174:177], v[92:95]
	v_mfma_f32_16x16x32_f16 v[174:177], v[112:115], v[190:193], v[80:83]
	v_mfma_f32_16x16x32_f16 v[178:181], v[206:209], v[190:193], v[76:79]
	s_setprio 0
	s_barrier
; #define LDA8(dst, b, h) _Pragma("unroll") for (int m = 0; m < 4; ++m) _Pragma("unroll") for (int k = 0; k < 2; ++k) \
;     dst[m][k] = *(const bf16x8*)((const char*)SA8(b, h) + lds_byte8(wr * 64 + m * 16 + fr, k * 32 + fq * 8))
; #define LDB8(dst, b, h) _Pragma("unroll") for (int n = 0; n < 2; ++n) _Pragma("unroll") for (int k = 0; k < 2; ++k) \
;     dst[n][k] = *(const bf16x8*)((const char*)SB8(b, h) + lds_byte8(wc * 32 + n * 16 + fr, k * 32 + fq * 8))
; #define WAIT_V8(n) asm volatile("s_waitcnt vmcnt(" #n ")" ::: "memory")
; #define WAIT_L8(n) asm volatile("s_waitcnt lgkmcnt(" #n ")" ::: "memory")
; #define BAR8 __builtin_amdgcn_s_barrier()
;     ...
;     LDA8(At, 0, 1); WAIT_V8(4); BAR8; WAIT_L8(0); MMA8(1, 0, At, B0); MMA8(1, 1, At, B1); BAR8; }
;   { LDB8(B0, 1, 0); LDA8(At, 1, 0); WAIT_V8(2); BAR8; WAIT_L8(0); MMA8(0, 0, At, B0); BAR8;
	s_nop 0
	ds_read_b128 v[76:79], v161 offset:16384
	ds_read_b128 v[80:83], v161 offset:17408
	ds_read_b128 v[92:95], v160 offset:16384
	ds_read_b128 v[96:99], v160 offset:17408
	ds_read_b128 v[182:185], v159 offset:16384
	ds_read_b128 v[186:189], v159 offset:17408
	ds_read_b128 v[190:193], v158 offset:16384
	ds_read_b128 v[194:197], v158 offset:17408
	s_waitcnt vmcnt(4)
	s_barrier
	s_waitcnt lgkmcnt(0)
	s_setprio 1
	s_waitcnt lgkmcnt(0)
	v_mfma_f32_16x16x32_f16 v[64:67], v[138:141], v[76:79], v[64:67]
	v_mfma_f32_16x16x32_f16 v[60:63], v[150:153], v[76:79], v[60:63]
	v_mfma_f32_16x16x32_f16 v[56:59], v[138:141], v[92:95], v[56:59]
	v_mfma_f32_16x16x32_f16 v[52:55], v[150:153], v[92:95], v[52:55]
	v_mfma_f32_16x16x32_f16 v[40:43], v[138:141], v[190:193], v[40:43]
	v_mfma_f32_16x16x32_f16 v[36:39], v[150:153], v[190:193], v[36:39]
	v_mfma_f32_16x16x32_f16 v[64:67], v[142:145], v[80:83], v[64:67]
	v_mfma_f32_16x16x32_f16 v[60:63], v[154:157], v[80:83], v[60:63]
	v_mfma_f32_16x16x32_f16 v[56:59], v[142:145], v[96:99], v[56:59]
	v_mfma_f32_16x16x32_f16 v[52:55], v[154:157], v[96:99], v[52:55]
	v_mfma_f32_16x16x32_f16 v[48:51], v[138:141], v[182:185], v[48:51]
	v_mfma_f32_16x16x32_f16 v[44:47], v[150:153], v[182:185], v[44:47]
	v_mfma_f32_16x16x32_f16 v[40:43], v[142:145], v[194:197], v[40:43]
	v_mfma_f32_16x16x32_f16 v[36:39], v[154:157], v[194:197], v[36:39]
	v_mfma_f32_16x16x32_f16 v[198:201], v[142:145], v[186:189], v[48:51]
	v_mfma_f32_16x16x32_f16 v[214:217], v[154:157], v[186:189], v[44:47]
	s_setprio 0
	s_setprio 1
	v_mfma_f32_16x16x32_f16 v[24:27], v[108:111], v[92:95], v[24:27]
	v_mfma_f32_16x16x32_f16 v[20:23], v[202:205], v[92:95], v[20:23]
	v_mfma_f32_16x16x32_f16 v[8:11], v[108:111], v[190:193], v[8:11]
	v_mfma_f32_16x16x32_f16 v[4:7], v[202:205], v[190:193], v[4:7]
	v_mfma_f32_16x16x32_f16 v[32:35], v[108:111], v[76:79], v[32:35]
	v_mfma_f32_16x16x32_f16 v[28:31], v[202:205], v[76:79], v[28:31]
	v_mfma_f32_16x16x32_f16 v[24:27], v[112:115], v[96:99], v[24:27]
	v_mfma_f32_16x16x32_f16 v[20:23], v[206:209], v[96:99], v[20:23]
	v_mfma_f32_16x16x32_f16 v[16:19], v[108:111], v[182:185], v[16:19]
	v_mfma_f32_16x16x32_f16 v[12:15], v[202:205], v[182:185], v[12:15]
	v_mfma_f32_16x16x32_f16 v[8:11], v[112:115], v[194:197], v[8:11]
	v_mfma_f32_16x16x32_f16 v[4:7], v[206:209], v[194:197], v[4:7]
	v_mfma_f32_16x16x32_f16 v[136:139], v[112:115], v[80:83], v[32:35]
	v_mfma_f32_16x16x32_f16 v[140:143], v[206:209], v[80:83], v[28:31]
	v_mfma_f32_16x16x32_f16 v[150:153], v[112:115], v[186:189], v[16:19]
	v_mfma_f32_16x16x32_f16 v[154:157], v[206:209], v[186:189], v[12:15]
	s_setprio 0
	s_barrier
	s_nop 0
	ds_read_b128 v[12:15], v163
	ds_read_b128 v[16:19], v163 offset:1024
	ds_read_b128 v[182:185], v163 offset:2048
	ds_read_b128 v[186:189], v163 offset:3072
	ds_read_b128 v[28:31], v161 offset:32768
	ds_read_b128 v[32:35], v161 offset:33792
	ds_read_b128 v[44:47], v160 offset:32768
	ds_read_b128 v[48:51], v160 offset:33792
	ds_read_b128 v[190:193], v159 offset:32768
	ds_read_b128 v[194:197], v159 offset:33792
	ds_read_b128 v[202:205], v158 offset:32768
	ds_read_b128 v[206:209], v158 offset:33792
	s_waitcnt vmcnt(2)
	s_barrier
	s_waitcnt lgkmcnt(0)
	s_setprio 1
	s_waitcnt lgkmcnt(0)
	v_mfma_f32_16x16x32_f16 v[76:79], v[12:15], v[28:31], v[128:131]
	v_mfma_f32_16x16x32_f16 v[128:131], v[16:19], v[32:35], v[76:79]
	v_mfma_f32_16x16x32_f16 v[76:79], v[182:185], v[28:31], v[124:127]
	v_mfma_f32_16x16x32_f16 v[124:127], v[186:189], v[32:35], v[76:79]
	v_mfma_f32_16x16x32_f16 v[76:79], v[12:15], v[44:47], v[120:123]
	v_mfma_f32_16x16x32_f16 v[112:115], v[16:19], v[48:51], v[76:79]
	v_mfma_f32_16x16x32_f16 v[76:79], v[182:185], v[44:47], v[116:119]
	v_mfma_f32_16x16x32_f16 v[108:111], v[186:189], v[48:51], v[76:79]
	v_mfma_f32_16x16x32_f16 v[76:79], v[12:15], v[190:193], v[132:135]
	v_mfma_f32_16x16x32_f16 v[96:99], v[16:19], v[194:197], v[76:79]
	v_mfma_f32_16x16x32_f16 v[76:79], v[182:185], v[190:193], v[170:173]
	v_mfma_f32_16x16x32_f16 v[92:95], v[186:189], v[194:197], v[76:79]
	v_mfma_f32_16x16x32_f16 v[76:79], v[12:15], v[202:205], v[104:107]
	v_mfma_f32_16x16x32_f16 v[80:83], v[16:19], v[206:209], v[76:79]
	v_mfma_f32_16x16x32_f16 v[76:79], v[182:185], v[202:205], v[100:103]
	v_mfma_f32_16x16x32_f16 v[76:79], v[186:189], v[206:209], v[76:79]
	s_setprio 0
	s_barrier
; #define LDA8(dst, b, h) _Pragma("unroll") for (int m = 0; m < 4; ++m) _Pragma("unroll") for (int k = 0; k < 2; ++k) \
;     dst[m][k] = *(const bf16x8*)((const char*)SA8(b, h) + lds_byte8(wr * 64 + m * 16 + fr, k * 32 + fq * 8))
; #define LDB8(dst, b, h) _Pragma("unroll") for (int n = 0; n < 2; ++n) _Pragma("unroll") for (int k = 0; k < 2; ++k) \
;     dst[n][k] = *(const bf16x8*)((const char*)SB8(b, h) + lds_byte8(wc * 32 + n * 16 + fr, k * 32 + fq * 8))
; #define WAIT_V8(n) asm volatile("s_waitcnt vmcnt(" #n ")" ::: "memory")
; #define WAIT_L8(n) asm volatile("s_waitcnt lgkmcnt(" #n ")" ::: "memory")
; #define BAR8 __builtin_amdgcn_s_barrier()
;     ...
;   { LDB8(B0, 1, 0); LDA8(At, 1, 0); WAIT_V8(2); BAR8; WAIT_L8(0); MMA8(0, 0, At, B0); BAR8;
;     LDB8(B1, 1, 1); WAIT_V8(0); BAR8; WAIT_L8(0); MMA8(0, 1, At, B1); BAR8;
;     LDA8(At, 1, 1); BAR8; WAIT_L8(0); MMA8(1, 0, At, B0); MMA8(1, 1, At, B1); BAR8; }
;   if (wr == 0) BAR8;
;   __syncthreads();
;     ...
;   if (t < 256) {
	ds_read_b128 v[132:135], v162
	ds_read_b128 v[168:171], v162 offset:1024
	ds_read_b128 v[218:221], v162 offset:2048
	ds_read_b128 v[226:229], v162 offset:3072
	s_waitcnt vmcnt(0)
	s_barrier
	s_waitcnt lgkmcnt(0)
	s_setprio 1
	s_waitcnt lgkmcnt(0)
	v_mfma_f32_16x16x32_f16 v[100:103], v[132:135], v[28:31], v[210:213]
	v_mfma_f32_16x16x32_f16 v[28:31], v[218:221], v[28:31], v[164:167]
	v_mfma_f32_16x16x32_f16 v[116:119], v[226:229], v[32:35], v[28:31]
	v_mfma_f32_16x16x32_f16 v[28:31], v[132:135], v[44:47], v[88:91]
	v_mfma_f32_16x16x32_f16 v[104:107], v[168:171], v[48:51], v[28:31]
	v_mfma_f32_16x16x32_f16 v[28:31], v[218:221], v[44:47], v[84:87]
	v_mfma_f32_16x16x32_f16 v[120:123], v[168:171], v[32:35], v[100:103]
	v_mfma_f32_16x16x32_f16 v[100:103], v[226:229], v[48:51], v[28:31]
	v_mfma_f32_16x16x32_f16 v[28:31], v[132:135], v[190:193], v[174:177]
	v_mfma_f32_16x16x32_f16 v[88:91], v[168:171], v[194:197], v[28:31]
	v_mfma_f32_16x16x32_f16 v[28:31], v[218:221], v[190:193], v[178:181]
	v_mfma_f32_16x16x32_f16 v[84:87], v[226:229], v[194:197], v[28:31]
	v_mfma_f32_16x16x32_f16 v[28:31], v[132:135], v[202:205], v[72:75]
	v_mfma_f32_16x16x32_f16 v[72:75], v[168:171], v[206:209], v[28:31]
	v_mfma_f32_16x16x32_f16 v[28:31], v[218:221], v[202:205], v[68:71]
	v_mfma_f32_16x16x32_f16 v[68:71], v[226:229], v[206:209], v[28:31]
	s_setprio 0
	s_barrier
	ds_read_b128 v[162:165], v161 offset:49152
	ds_read_b128 v[172:175], v161 offset:50176
	ds_read_b128 v[176:179], v160 offset:49152
	ds_read_b128 v[190:193], v160 offset:50176
	ds_read_b128 v[194:197], v159 offset:49152
	ds_read_b128 v[202:205], v159 offset:50176
	ds_read_b128 v[206:209], v158 offset:49152
	ds_read_b128 v[158:161], v158 offset:50176
	s_barrier
	s_waitcnt lgkmcnt(0)
	s_setprio 1
	s_waitcnt lgkmcnt(0)
	v_mfma_f32_16x16x32_f16 v[28:31], v[12:15], v[162:165], v[64:67]
	v_mfma_f32_16x16x32_f16 v[64:67], v[16:19], v[172:175], v[28:31]
	v_mfma_f32_16x16x32_f16 v[28:31], v[182:185], v[162:165], v[60:63]
	v_mfma_f32_16x16x32_f16 v[60:63], v[186:189], v[172:175], v[28:31]
	v_mfma_f32_16x16x32_f16 v[28:31], v[12:15], v[176:179], v[56:59]
	v_mfma_f32_16x16x32_f16 v[48:51], v[16:19], v[190:193], v[28:31]
	v_mfma_f32_16x16x32_f16 v[28:31], v[182:185], v[176:179], v[52:55]
	v_mfma_f32_16x16x32_f16 v[44:47], v[186:189], v[190:193], v[28:31]
	v_mfma_f32_16x16x32_f16 v[28:31], v[12:15], v[194:197], v[198:201]
	v_mfma_f32_16x16x32_f16 v[12:15], v[12:15], v[206:209], v[40:43]
	v_mfma_f32_16x16x32_f16 v[32:35], v[16:19], v[202:205], v[28:31]
	v_mfma_f32_16x16x32_f16 v[28:31], v[182:185], v[194:197], v[214:217]
	v_mfma_f32_16x16x32_f16 v[16:19], v[16:19], v[158:161], v[12:15]
	v_mfma_f32_16x16x32_f16 v[12:15], v[182:185], v[206:209], v[36:39]
	v_mfma_f32_16x16x32_f16 v[28:31], v[186:189], v[202:205], v[28:31]
	v_mfma_f32_16x16x32_f16 v[12:15], v[186:189], v[158:161], v[12:15]
	s_setprio 0
	s_setprio 1
	v_mfma_f32_16x16x32_f16 v[36:39], v[132:135], v[162:165], v[136:139]
	v_mfma_f32_16x16x32_f16 v[56:59], v[168:171], v[172:175], v[36:39]
	v_mfma_f32_16x16x32_f16 v[36:39], v[218:221], v[162:165], v[140:143]
	v_mfma_f32_16x16x32_f16 v[20:23], v[218:221], v[176:179], v[20:23]
	v_mfma_f32_16x16x32_f16 v[52:55], v[226:229], v[172:175], v[36:39]
	v_mfma_f32_16x16x32_f16 v[24:27], v[132:135], v[176:179], v[24:27]
	v_mfma_f32_16x16x32_f16 v[36:39], v[226:229], v[190:193], v[20:23]
	v_mfma_f32_16x16x32_f16 v[20:23], v[132:135], v[194:197], v[150:153]
	v_mfma_f32_16x16x32_f16 v[40:43], v[168:171], v[190:193], v[24:27]
	v_mfma_f32_16x16x32_f16 v[24:27], v[168:171], v[202:205], v[20:23]
	v_mfma_f32_16x16x32_f16 v[20:23], v[218:221], v[194:197], v[154:157]
	v_mfma_f32_16x16x32_f16 v[8:11], v[132:135], v[206:209], v[8:11]
	v_mfma_f32_16x16x32_f16 v[4:7], v[218:221], v[206:209], v[4:7]
	v_mfma_f32_16x16x32_f16 v[20:23], v[226:229], v[202:205], v[20:23]
	v_mfma_f32_16x16x32_f16 v[8:11], v[168:171], v[158:161], v[8:11]
	v_mfma_f32_16x16x32_f16 v[4:7], v[226:229], v[158:161], v[4:7]
	s_setprio 0
	s_movk_i32 s1, 0x100
	v_cmp_gt_u32_e32 vcc, s1, v3
	s_barrier
	s_and_saveexec_b64 s[8:9], vcc
	s_cbranch_execz .LBB0_1262
	s_barrier
